# E33: sample-FoX tile loop (single computing wave): K/bias LDS reads and transposed V reads issued ahead into private registers with counted waits; on E30
# baseline (speedup 1.0000x reference)
.LBB0_1457:
	s_cmp_le_i32 s10, s9
	s_cselect_b64 s[14:15], -1, 0
	s_and_b64 s[14:15], s[78:79], s[14:15]
	s_andn2_b64 vcc, exec, s[14:15]
	s_cbranch_vccnz .LBB0_1463
	s_bitcmp1_b32 s11, 0
	s_cselect_b32 s13, 0, 0x5400
	s_add_i32 s13, s13, 0
	ds_read_b128 v[50:53], v137
	ds_read_b128 v[54:57], v137 offset:32
	ds_read_b128 v[58:61], v137 offset:64
	ds_read_b128 v[62:65], v137 offset:96
	v_add3_u32 v2, s13, v214, v186
	v_add3_u32 v242, s13, v123, v130
	ds_read_b128 v[196:199], v2
	ds_read_b128 v[200:203], v2 offset:32
	ds_read_b128 v[204:207], v2 offset:64
	ds_read_b128 v[208:211], v2 offset:96
	ds_read_b128 v[66:69], v137 offset:128
	ds_read_b128 v[70:73], v137 offset:160
	ds_read_b128 v[74:77], v137 offset:192
	ds_read_b128 v[78:81], v137 offset:224
	s_add_i32 s14, s10, 63
	s_cmp_le_i32 s14, s6
	s_waitcnt lgkmcnt(7)
	v_mfma_f32_32x32x16_bf16 v[50:65], v[196:199], v[94:97], v[50:65]
	ds_read_b128 v[226:229], v2 offset:4608
	s_waitcnt lgkmcnt(7)
	v_mfma_f32_32x32x16_bf16 v[50:65], v[200:203], v[90:93], v[50:65]
	ds_read_b128 v[230:233], v2 offset:4640
	s_waitcnt lgkmcnt(7)
	v_mfma_f32_32x32x16_bf16 v[50:65], v[204:207], v[86:89], v[50:65]
	ds_read_b128 v[234:237], v2 offset:4672
	s_waitcnt lgkmcnt(7)
	v_mfma_f32_32x32x16_bf16 v[50:65], v[208:211], v[82:85], v[50:65]
	ds_read_b128 v[238:241], v2 offset:4704
	s_waitcnt lgkmcnt(3)
	v_mfma_f32_32x32x16_bf16 v[66:81], v[226:229], v[94:97], v[66:81]
	s_waitcnt lgkmcnt(2)
	v_mfma_f32_32x32x16_bf16 v[66:81], v[230:233], v[90:93], v[66:81]
	s_waitcnt lgkmcnt(1)
	v_mfma_f32_32x32x16_bf16 v[66:81], v[234:237], v[86:89], v[66:81]
	s_waitcnt lgkmcnt(0)
	v_mfma_f32_32x32x16_bf16 v[66:81], v[238:241], v[82:85], v[66:81]
	s_cbranch_scc1 .LBB0_1460
	v_cmp_gt_i32_e32 vcc, 0, v134
	v_cmp_gt_i32_e64 s[18:19], 1, v134
	s_and_b64 vcc, s[18:19], vcc
	v_cndmask_b32_e32 v50, v50, v190, vcc
	v_cmp_lt_i32_e32 vcc, 1, v134
	v_cmp_gt_i32_e64 s[46:47], 58, v134
	v_cmp_gt_i32_e64 s[48:49], 59, v134
	v_cndmask_b32_e32 v52, v190, v52, vcc
	v_cmp_lt_i32_e32 vcc, 2, v134
	v_cmp_gt_i32_e64 s[44:45], 57, v134
	s_and_b64 s[46:47], s[48:49], s[46:47]
	v_cndmask_b32_e32 v53, v190, v53, vcc
	v_cmp_lt_i32_e32 vcc, 7, v134
	v_cmp_gt_i32_e64 s[42:43], 56, v134
	s_and_b64 s[44:45], s[46:47], s[44:45]
	v_cndmask_b32_e32 v54, v190, v54, vcc
	v_cmp_lt_i32_e32 vcc, 8, v134
	v_cmp_gt_i32_e64 s[40:41], 51, v134
	s_and_b64 s[42:43], s[44:45], s[42:43]
	v_cndmask_b32_e32 v55, v190, v55, vcc
	v_cmp_lt_i32_e32 vcc, 9, v134
	v_cmp_gt_i32_e64 s[38:39], 50, v134
	s_and_b64 s[40:41], s[42:43], s[40:41]
	v_cndmask_b32_e32 v56, v190, v56, vcc
	v_cmp_lt_i32_e32 vcc, 10, v134
	v_cmp_gt_i32_e64 s[36:37], 49, v134
	s_and_b64 s[38:39], s[40:41], s[38:39]
	v_cndmask_b32_e32 v57, v190, v57, vcc
	v_cmp_lt_i32_e32 vcc, 15, v134
	v_cmp_gt_i32_e64 s[34:35], 48, v134
	s_and_b64 s[36:37], s[38:39], s[36:37]
	v_cndmask_b32_e32 v58, v190, v58, vcc
	v_cmp_lt_i32_e32 vcc, 16, v134
	v_cmp_gt_i32_e64 s[30:31], 43, v134
	s_and_b64 s[34:35], s[36:37], s[34:35]
	v_cndmask_b32_e32 v59, v190, v59, vcc
	v_cmp_lt_i32_e32 vcc, 17, v134
	v_cmp_gt_i32_e64 s[28:29], 42, v134
	s_and_b64 s[30:31], s[34:35], s[30:31]
	v_cndmask_b32_e32 v60, v190, v60, vcc
	v_cmp_lt_i32_e32 vcc, 18, v134
	v_cmp_gt_i32_e64 s[26:27], 41, v134
	s_and_b64 s[28:29], s[30:31], s[28:29]
	v_cndmask_b32_e32 v61, v190, v61, vcc
	v_cmp_lt_i32_e32 vcc, 23, v134
	v_cmp_gt_i32_e64 s[24:25], 40, v134
	s_and_b64 s[26:27], s[28:29], s[26:27]
	v_cndmask_b32_e32 v62, v190, v62, vcc
	v_cmp_lt_i32_e32 vcc, 24, v134
	v_cmp_gt_i32_e64 s[22:23], 35, v134
	s_and_b64 s[24:25], s[26:27], s[24:25]
	v_cndmask_b32_e32 v63, v190, v63, vcc
	v_cmp_lt_i32_e32 vcc, 25, v134
	v_cmp_gt_i32_e64 s[20:21], 34, v134
	s_and_b64 s[22:23], s[24:25], s[22:23]
	v_cndmask_b32_e64 v51, v51, v190, s[18:19]
	v_cndmask_b32_e32 v64, v190, v64, vcc
	v_cmp_lt_i32_e32 vcc, 26, v134
	v_cmp_gt_i32_e64 s[18:19], 33, v134
	s_and_b64 s[20:21], s[22:23], s[20:21]
	v_cndmask_b32_e32 v2, v190, v65, vcc
	v_cmp_gt_i32_e32 vcc, 32, v134
	s_and_b64 s[18:19], s[20:21], s[18:19]
	s_and_b64 vcc, s[18:19], vcc
	v_cndmask_b32_e64 v81, v81, v190, s[48:49]
	v_cndmask_b32_e64 v80, v80, v190, s[46:47]
	v_cndmask_b32_e64 v79, v79, v190, s[44:45]
	v_cndmask_b32_e64 v78, v78, v190, s[42:43]
	v_cndmask_b32_e64 v77, v77, v190, s[40:41]
	v_cndmask_b32_e64 v76, v76, v190, s[38:39]
	v_cndmask_b32_e64 v75, v75, v190, s[36:37]
	v_cndmask_b32_e64 v74, v74, v190, s[34:35]
	v_cndmask_b32_e64 v73, v73, v190, s[30:31]
	v_cndmask_b32_e64 v72, v72, v190, s[28:29]
	v_cndmask_b32_e64 v71, v71, v190, s[26:27]
	v_cndmask_b32_e64 v70, v70, v190, s[24:25]
	v_cndmask_b32_e64 v69, v69, v190, s[22:23]
	v_cndmask_b32_e64 v68, v68, v190, s[20:21]
	v_cndmask_b32_e64 v67, v67, v190, s[18:19]
	v_cndmask_b32_e32 v65, v65, v2, vcc
	v_cndmask_b32_e32 v66, v66, v190, vcc
.LBB0_1460:
	ds_read_b64_tr_b16 v[196:197], v242 offset:9216
	ds_read_b64_tr_b16 v[198:199], v242 offset:10752
	ds_read_b64_tr_b16 v[200:201], v242 offset:9280
	ds_read_b64_tr_b16 v[202:203], v242 offset:10816
	ds_read_b64_tr_b16 v[204:205], v242 offset:12288
	ds_read_b64_tr_b16 v[206:207], v242 offset:13824
	ds_read_b64_tr_b16 v[208:209], v242 offset:12352
	ds_read_b64_tr_b16 v[210:211], v242 offset:13888
	ds_read_b64_tr_b16 v[226:227], v242 offset:15360
	ds_read_b64_tr_b16 v[228:229], v242 offset:16896
	ds_read_b64_tr_b16 v[230:231], v242 offset:15424
	ds_read_b64_tr_b16 v[232:233], v242 offset:16960
	s_nop 10
	v_max_f32_e32 v16, v67, v67
	v_max_f32_e32 v17, v66, v66
	v_max_f32_e32 v16, v17, v16
	v_max3_f32 v2, v50, v51, v52
	v_max3_f32 v16, v16, v68, v69
	v_max3_f32 v2, v2, v53, v54
	v_max3_f32 v16, v16, v70, v71
	v_max3_f32 v2, v2, v55, v56
	v_max3_f32 v16, v16, v72, v73
	v_max3_f32 v2, v2, v57, v58
	v_max3_f32 v16, v16, v74, v75
	v_max3_f32 v2, v2, v59, v60
	v_max3_f32 v16, v16, v76, v77
	v_max3_f32 v2, v2, v61, v62
	v_max3_f32 v16, v16, v78, v79
	v_max3_f32 v2, v2, v63, v64
	v_max3_f32 v16, v16, v80, v81
	v_max3_f32 v2, v2, v65, v16
	v_mov_b32_e32 v16, v2
	s_nop 1
	v_permlane32_swap_b32_e32 v2, v16
	v_max_f32_e32 v16, v16, v16
	v_max_f32_e32 v2, v2, v2
	v_max_f32_e32 v2, v2, v16
	v_add_f32_e32 v16, 0x41a00000, v122
	v_cmp_gt_f32_e32 vcc, v2, v16
	s_cbranch_vccz .LBB0_1462
	v_max_f32_e32 v2, v2, v2
	v_max_f32_e32 v16, v122, v122
	v_max_f32_e32 v16, v16, v2
	v_sub_f32_e32 v2, v122, v16
	v_exp_f32_e32 v2, v2
	v_mov_b32_e32 v122, v16
	v_pk_mul_f32 v[48:49], v[48:49], v[2:3] op_sel_hi:[1,0]
	v_pk_mul_f32 v[46:47], v[46:47], v[2:3] op_sel_hi:[1,0]
	v_pk_mul_f32 v[44:45], v[44:45], v[2:3] op_sel_hi:[1,0]
	v_pk_mul_f32 v[42:43], v[42:43], v[2:3] op_sel_hi:[1,0]
	v_pk_mul_f32 v[40:41], v[40:41], v[2:3] op_sel_hi:[1,0]
	v_pk_mul_f32 v[38:39], v[38:39], v[2:3] op_sel_hi:[1,0]
	v_pk_mul_f32 v[36:37], v[36:37], v[2:3] op_sel_hi:[1,0]
	v_pk_mul_f32 v[34:35], v[34:35], v[2:3] op_sel_hi:[1,0]
	v_pk_mul_f32 v[32:33], v[32:33], v[2:3] op_sel_hi:[1,0]
	v_pk_mul_f32 v[30:31], v[30:31], v[2:3] op_sel_hi:[1,0]
	v_pk_mul_f32 v[28:29], v[28:29], v[2:3] op_sel_hi:[1,0]
	v_pk_mul_f32 v[26:27], v[26:27], v[2:3] op_sel_hi:[1,0]
	v_pk_mul_f32 v[24:25], v[24:25], v[2:3] op_sel_hi:[1,0]
	v_pk_mul_f32 v[22:23], v[22:23], v[2:3] op_sel_hi:[1,0]
	v_pk_mul_f32 v[20:21], v[20:21], v[2:3] op_sel_hi:[1,0]
	v_pk_mul_f32 v[18:19], v[18:19], v[2:3] op_sel_hi:[1,0]
	v_mul_f32_e32 v119, v119, v2
.LBB0_1462:
	v_pk_add_f32 v[16:17], v[50:51], v[122:123] op_sel_hi:[1,0] neg_lo:[0,1] neg_hi:[0,1]
	v_pk_add_f32 v[50:51], v[52:53], v[122:123] op_sel_hi:[1,0] neg_lo:[0,1] neg_hi:[0,1]
	v_exp_f32_e32 v138, v16
	v_exp_f32_e32 v139, v17
	v_exp_f32_e32 v140, v50
	v_exp_f32_e32 v141, v51
	v_pk_add_f32 v[50:51], v[54:55], v[122:123] op_sel_hi:[1,0] neg_lo:[0,1] neg_hi:[0,1]
	v_pk_add_f32 v[16:17], v[138:139], 0 op_sel_hi:[1,0]
	v_exp_f32_e32 v142, v50
	v_exp_f32_e32 v143, v51
	v_pk_add_f32 v[50:51], v[56:57], v[122:123] op_sel_hi:[1,0] neg_lo:[0,1] neg_hi:[0,1]
	v_pk_add_f32 v[16:17], v[140:141], v[16:17]
	v_exp_f32_e32 v144, v50
	v_exp_f32_e32 v145, v51
	v_pk_add_f32 v[50:51], v[58:59], v[122:123] op_sel_hi:[1,0] neg_lo:[0,1] neg_hi:[0,1]
	v_pk_add_f32 v[16:17], v[142:143], v[16:17]
	v_exp_f32_e32 v124, v50
	v_exp_f32_e32 v125, v51
	v_pk_add_f32 v[50:51], v[60:61], v[122:123] op_sel_hi:[1,0] neg_lo:[0,1] neg_hi:[0,1]
	v_pk_add_f32 v[16:17], v[144:145], v[16:17]
	v_exp_f32_e32 v126, v50
	v_exp_f32_e32 v127, v51
	v_pk_add_f32 v[50:51], v[62:63], v[122:123] op_sel_hi:[1,0] neg_lo:[0,1] neg_hi:[0,1]
	v_pk_add_f32 v[16:17], v[124:125], v[16:17]
	v_exp_f32_e32 v128, v50
	v_exp_f32_e32 v129, v51
	v_pk_add_f32 v[50:51], v[64:65], v[122:123] op_sel_hi:[1,0] neg_lo:[0,1] neg_hi:[0,1]
	v_pk_add_f32 v[16:17], v[126:127], v[16:17]
	v_exp_f32_e32 v64, v50
	v_exp_f32_e32 v65, v51
	v_pk_add_f32 v[50:51], v[66:67], v[122:123] op_sel_hi:[1,0] neg_lo:[0,1] neg_hi:[0,1]
	v_pk_add_f32 v[16:17], v[128:129], v[16:17]
	v_exp_f32_e32 v56, v50
	v_exp_f32_e32 v57, v51
	v_pk_add_f32 v[50:51], v[68:69], v[122:123] op_sel_hi:[1,0] neg_lo:[0,1] neg_hi:[0,1]
	v_pk_add_f32 v[16:17], v[64:65], v[16:17]
	v_exp_f32_e32 v58, v50
	v_exp_f32_e32 v59, v51
	v_pk_add_f32 v[50:51], v[70:71], v[122:123] op_sel_hi:[1,0] neg_lo:[0,1] neg_hi:[0,1]
	v_pk_add_f32 v[16:17], v[56:57], v[16:17]
	v_exp_f32_e32 v60, v50
	v_exp_f32_e32 v61, v51
	v_pk_add_f32 v[50:51], v[72:73], v[122:123] op_sel_hi:[1,0] neg_lo:[0,1] neg_hi:[0,1]
	v_pk_add_f32 v[16:17], v[58:59], v[16:17]
	v_exp_f32_e32 v62, v50
	v_exp_f32_e32 v63, v51
	v_pk_add_f32 v[16:17], v[60:61], v[16:17]
	v_cvt_pk_bf16_f32 v68, v142, v143
	v_cvt_pk_bf16_f32 v69, v144, v145
	v_pk_add_f32 v[50:51], v[62:63], v[16:17]
	v_pk_add_f32 v[16:17], v[74:75], v[122:123] op_sel_hi:[1,0] neg_lo:[0,1] neg_hi:[0,1]
	v_add3_u32 v74, s13, v123, v130
	v_exp_f32_e32 v16, v16
	v_exp_f32_e32 v17, v17
	v_cvt_pk_bf16_f32 v56, v56, v57
	v_cvt_pk_bf16_f32 v57, v58, v59
	v_pk_add_f32 v[52:53], v[16:17], v[50:51]
	v_pk_add_f32 v[50:51], v[76:77], v[122:123] op_sel_hi:[1,0] neg_lo:[0,1] neg_hi:[0,1]
	v_cvt_pk_bf16_f32 v58, v60, v61
	v_exp_f32_e32 v50, v50
	v_exp_f32_e32 v51, v51
	v_cvt_pk_bf16_f32 v59, v62, v63
	v_pk_add_f32 v[54:55], v[50:51], v[52:53]
	v_pk_add_f32 v[52:53], v[78:79], v[122:123] op_sel_hi:[1,0] neg_lo:[0,1] neg_hi:[0,1]
	s_nop 0
	v_exp_f32_e32 v52, v52
	v_exp_f32_e32 v53, v53
	s_nop 0
	v_pk_add_f32 v[66:67], v[52:53], v[54:55]
	v_pk_add_f32 v[54:55], v[80:81], v[122:123] op_sel_hi:[1,0] neg_lo:[0,1] neg_hi:[0,1]
	s_nop 0
	v_exp_f32_e32 v54, v54
	v_exp_f32_e32 v55, v55
	s_nop 0
	v_pk_add_f32 v[66:67], v[54:55], v[66:67]
	s_nop 0
	v_add_f32_e32 v2, v66, v67
	v_cvt_pk_bf16_f32 v66, v138, v139
	v_cvt_pk_bf16_f32 v67, v140, v141
	v_add_f32_e32 v119, v119, v2
	s_waitcnt lgkmcnt(10)
	v_mfma_f32_32x32x16_bf16 v[34:49], v[196:199], v[66:69], v[34:49]
	ds_read_b64_tr_b16 v[234:235], v242 offset:18432
	ds_read_b64_tr_b16 v[236:237], v242 offset:19968
	s_waitcnt lgkmcnt(10)
	v_mfma_f32_32x32x16_bf16 v[18:33], v[200:203], v[66:69], v[18:33]
	ds_read_b64_tr_b16 v[238:239], v242 offset:18496
	ds_read_b64_tr_b16 v[240:241], v242 offset:20032
	v_cvt_pk_bf16_f32 v66, v124, v125
	v_cvt_pk_bf16_f32 v67, v126, v127
	v_cvt_pk_bf16_f32 v68, v128, v129
	v_cvt_pk_bf16_f32 v69, v64, v65
	s_nop 0
	s_waitcnt lgkmcnt(10)
	v_mfma_f32_32x32x16_bf16 v[34:49], v[204:207], v[66:69], v[34:49]
	s_waitcnt lgkmcnt(8)
	v_mfma_f32_32x32x16_bf16 v[18:33], v[208:211], v[66:69], v[18:33]
	s_waitcnt lgkmcnt(6)
	v_mfma_f32_32x32x16_bf16 v[34:49], v[226:229], v[56:59], v[34:49]
	s_waitcnt lgkmcnt(4)
	v_mfma_f32_32x32x16_bf16 v[18:33], v[230:233], v[56:59], v[18:33]
	v_cvt_pk_bf16_f32 v57, v50, v51
	v_cvt_pk_bf16_f32 v58, v52, v53
	v_cvt_pk_bf16_f32 v56, v16, v17
	v_cvt_pk_bf16_f32 v59, v54, v55
	s_nop 0
	s_waitcnt lgkmcnt(2)
	v_mfma_f32_32x32x16_bf16 v[34:49], v[234:237], v[56:59], v[34:49]
	s_waitcnt lgkmcnt(0)
	v_mfma_f32_32x32x16_bf16 v[18:33], v[238:241], v[56:59], v[18:33]
